# v29 + loop-carried pointer/counter updates of four bf16 K-loops moved into the last compute segment's MFMA stream
# baseline (speedup 1.0000x reference)
.LBB0_134:
	s_add_u32 s0, s34, 0xfff00080
	s_addc_u32 s1, s35, -1
	s_cmp_eq_u32 s60, 60
	s_cselect_b32 s39, s12, s1
	s_cselect_b32 s38, s13, s0
	s_cselect_b32 s37, s15, s59
	s_cselect_b32 s36, s57, s58
	s_add_i32 m0, s29, 0xc000
	ds_read_b128 v[148:151], v156
	global_load_lds_dwordx4 v140, s[34:35]
	s_add_i32 m0, s29, 0xe000
	ds_read_b128 v[160:163], v156 offset:1024
	global_load_lds_dwordx4 v142, s[34:35]
	ds_read_b128 v[164:167], v156 offset:2048
	ds_read_b128 v[168:171], v156 offset:3072
	ds_read_b128 v[172:175], v157
	ds_read_b128 v[176:179], v157 offset:1024
	ds_read_b128 v[180:183], v157 offset:2048
	ds_read_b128 v[184:187], v157 offset:3072
	ds_read_b128 v[188:191], v158
	ds_read_b128 v[192:195], v158 offset:1024
	ds_read_b128 v[196:199], v158 offset:2048
	ds_read_b128 v[200:203], v158 offset:3072
	ds_read_b128 v[208:211], v158 offset:4096
	ds_read_b128 v[212:215], v158 offset:5120
	ds_read_b128 v[216:219], v158 offset:6144
	ds_read_b128 v[220:223], v158 offset:7168
	s_waitcnt vmcnt(8) lgkmcnt(0)
	s_setprio 3
	s_barrier
	v_mfma_f32_16x16x32_bf16 v[124:127], v[148:151], v[188:191], v[124:127]
	v_mfma_f32_16x16x32_bf16 v[120:123], v[164:167], v[188:191], v[120:123]
	v_mfma_f32_16x16x32_bf16 v[108:111], v[148:151], v[196:199], v[108:111]
	v_mfma_f32_16x16x32_bf16 v[104:107], v[164:167], v[196:199], v[104:107]
	v_mfma_f32_16x16x32_bf16 v[92:95], v[148:151], v[208:211], v[92:95]
	v_mfma_f32_16x16x32_bf16 v[88:91], v[164:167], v[208:211], v[88:91]
	v_mfma_f32_16x16x32_bf16 v[76:79], v[148:151], v[216:219], v[76:79]
	v_mfma_f32_16x16x32_bf16 v[72:75], v[164:167], v[216:219], v[72:75]
	v_mfma_f32_16x16x32_bf16 v[124:127], v[160:163], v[192:195], v[124:127]
	v_mfma_f32_16x16x32_bf16 v[120:123], v[168:171], v[192:195], v[120:123]
	v_mfma_f32_16x16x32_bf16 v[108:111], v[160:163], v[200:203], v[108:111]
	v_mfma_f32_16x16x32_bf16 v[104:107], v[168:171], v[200:203], v[104:107]
	v_mfma_f32_16x16x32_bf16 v[92:95], v[160:163], v[212:215], v[92:95]
	v_mfma_f32_16x16x32_bf16 v[88:91], v[168:171], v[212:215], v[88:91]
	v_mfma_f32_16x16x32_bf16 v[76:79], v[160:163], v[220:223], v[76:79]
	v_mfma_f32_16x16x32_bf16 v[72:75], v[168:171], v[220:223], v[72:75]
	v_mfma_f32_16x16x32_bf16 v[116:119], v[172:175], v[188:191], v[116:119]
	v_mfma_f32_16x16x32_bf16 v[112:115], v[180:183], v[188:191], v[112:115]
	v_mfma_f32_16x16x32_bf16 v[100:103], v[172:175], v[196:199], v[100:103]
	v_mfma_f32_16x16x32_bf16 v[96:99], v[180:183], v[196:199], v[96:99]
	v_mfma_f32_16x16x32_bf16 v[84:87], v[172:175], v[208:211], v[84:87]
	v_mfma_f32_16x16x32_bf16 v[80:83], v[180:183], v[208:211], v[80:83]
	v_mfma_f32_16x16x32_bf16 v[68:71], v[172:175], v[216:219], v[68:71]
	v_mfma_f32_16x16x32_bf16 v[64:67], v[180:183], v[216:219], v[64:67]
	v_mfma_f32_16x16x32_bf16 v[116:119], v[176:179], v[192:195], v[116:119]
	v_mfma_f32_16x16x32_bf16 v[112:115], v[184:187], v[192:195], v[112:115]
	v_mfma_f32_16x16x32_bf16 v[100:103], v[176:179], v[200:203], v[100:103]
	v_mfma_f32_16x16x32_bf16 v[96:99], v[184:187], v[200:203], v[96:99]
	v_mfma_f32_16x16x32_bf16 v[84:87], v[176:179], v[212:215], v[84:87]
	v_mfma_f32_16x16x32_bf16 v[80:83], v[184:187], v[212:215], v[80:83]
	v_mfma_f32_16x16x32_bf16 v[68:71], v[176:179], v[220:223], v[68:71]
	v_mfma_f32_16x16x32_bf16 v[64:67], v[184:187], v[220:223], v[64:67]
	s_barrier
	s_setprio 0
	s_add_i32 s0, s51, s41
	s_mov_b32 m0, s0
	ds_read_b128 v[188:191], v158 offset:16384
	global_load_lds_dwordx4 v132, s[36:37]
	s_add_i32 m0, s0, 0x2000
	ds_read_b128 v[192:195], v158 offset:17408
	global_load_lds_dwordx4 v136, s[36:37]
	s_add_u32 s62, s36, 0x100000
	s_addc_u32 s63, s37, 0
	s_add_i32 s0, s52, s41
	s_mov_b32 m0, s0
	ds_read_b128 v[196:199], v158 offset:18432
	global_load_lds_dwordx4 v132, s[62:63]
	s_add_i32 m0, s0, 0x2000
	ds_read_b128 v[200:203], v158 offset:19456
	global_load_lds_dwordx4 v136, s[62:63]
	s_mov_b32 m0, s29
	ds_read_b128 v[208:211], v158 offset:20480
	global_load_lds_dwordx4 v130, s[38:39]
	s_mov_b32 m0, s31
	ds_read_b128 v[212:215], v158 offset:21504
	global_load_lds_dwordx4 v134, s[38:39]
	ds_read_b128 v[216:219], v158 offset:22528
	ds_read_b128 v[220:223], v158 offset:23552
	s_waitcnt vmcnt(8) lgkmcnt(0)
	s_setprio 3
	s_barrier
	v_mfma_f32_16x16x32_bf16 v[60:63], v[148:151], v[188:191], v[60:63]
	v_mfma_f32_16x16x32_bf16 v[56:59], v[164:167], v[188:191], v[56:59]
	v_mfma_f32_16x16x32_bf16 v[44:47], v[148:151], v[196:199], v[44:47]
	v_mfma_f32_16x16x32_bf16 v[40:43], v[164:167], v[196:199], v[40:43]
	v_mfma_f32_16x16x32_bf16 v[28:31], v[148:151], v[208:211], v[28:31]
	v_mfma_f32_16x16x32_bf16 v[24:27], v[164:167], v[208:211], v[24:27]
	v_mfma_f32_16x16x32_bf16 v[12:15], v[148:151], v[216:219], v[12:15]
	v_mfma_f32_16x16x32_bf16 v[8:11], v[164:167], v[216:219], v[8:11]
	v_mfma_f32_16x16x32_bf16 v[60:63], v[160:163], v[192:195], v[60:63]
	v_mfma_f32_16x16x32_bf16 v[56:59], v[168:171], v[192:195], v[56:59]
	v_mfma_f32_16x16x32_bf16 v[44:47], v[160:163], v[200:203], v[44:47]
	v_mfma_f32_16x16x32_bf16 v[40:43], v[168:171], v[200:203], v[40:43]
	v_mfma_f32_16x16x32_bf16 v[28:31], v[160:163], v[212:215], v[28:31]
	v_mfma_f32_16x16x32_bf16 v[24:27], v[168:171], v[212:215], v[24:27]
	v_mfma_f32_16x16x32_bf16 v[12:15], v[160:163], v[220:223], v[12:15]
	v_mfma_f32_16x16x32_bf16 v[8:11], v[168:171], v[220:223], v[8:11]
	v_mfma_f32_16x16x32_bf16 v[52:55], v[172:175], v[188:191], v[52:55]
	v_mfma_f32_16x16x32_bf16 v[48:51], v[180:183], v[188:191], v[48:51]
	v_mfma_f32_16x16x32_bf16 v[36:39], v[172:175], v[196:199], v[36:39]
	v_mfma_f32_16x16x32_bf16 v[32:35], v[180:183], v[196:199], v[32:35]
	v_mfma_f32_16x16x32_bf16 v[20:23], v[172:175], v[208:211], v[20:23]
	v_mfma_f32_16x16x32_bf16 v[16:19], v[180:183], v[208:211], v[16:19]
	v_mfma_f32_16x16x32_bf16 v[4:7], v[172:175], v[216:219], v[4:7]
	v_mfma_f32_16x16x32_bf16 v[0:3], v[180:183], v[216:219], v[0:3]
	v_mfma_f32_16x16x32_bf16 v[52:55], v[176:179], v[192:195], v[52:55]
	v_mfma_f32_16x16x32_bf16 v[48:51], v[184:187], v[192:195], v[48:51]
	v_mfma_f32_16x16x32_bf16 v[36:39], v[176:179], v[200:203], v[36:39]
	v_mfma_f32_16x16x32_bf16 v[32:35], v[184:187], v[200:203], v[32:35]
	v_mfma_f32_16x16x32_bf16 v[20:23], v[176:179], v[212:215], v[20:23]
	v_mfma_f32_16x16x32_bf16 v[16:19], v[184:187], v[212:215], v[16:19]
	v_mfma_f32_16x16x32_bf16 v[4:7], v[176:179], v[220:223], v[4:7]
	v_mfma_f32_16x16x32_bf16 v[0:3], v[184:187], v[220:223], v[0:3]
	s_barrier
	s_setprio 0
	s_add_i32 s0, 0, 0x18000
	s_add_i32 s1, 0, 0x1c000
	ds_read_b128 v[148:151], v228
	ds_read_b128 v[160:163], v228 offset:1024
	ds_read_b128 v[164:167], v228 offset:2048
	ds_read_b128 v[168:171], v228 offset:3072
	ds_read_b128 v[172:175], v229
	ds_read_b128 v[176:179], v229 offset:1024
	ds_read_b128 v[180:183], v229 offset:2048
	ds_read_b128 v[184:187], v229 offset:3072
	s_add_u32 s38, s38, 0x100000
	s_addc_u32 s39, s39, 0
	s_mov_b32 m0, s42
	ds_read_b128 v[188:191], v158 offset:32768
	global_load_lds_dwordx4 v130, s[38:39]
	s_mov_b32 m0, s43
	ds_read_b128 v[192:195], v158 offset:33792
	global_load_lds_dwordx4 v134, s[38:39]
	ds_read_b128 v[196:199], v158 offset:34816
	ds_read_b128 v[200:203], v158 offset:35840
	ds_read_b128 v[208:211], v158 offset:36864
	ds_read_b128 v[212:215], v158 offset:37888
	ds_read_b128 v[216:219], v158 offset:38912
	ds_read_b128 v[220:223], v158 offset:39936
	s_waitcnt vmcnt(8) lgkmcnt(0)
	s_setprio 3
	s_barrier
	v_mfma_f32_16x16x32_bf16 v[124:127], v[148:151], v[188:191], v[124:127]
	v_mfma_f32_16x16x32_bf16 v[120:123], v[164:167], v[188:191], v[120:123]
	v_mfma_f32_16x16x32_bf16 v[108:111], v[148:151], v[196:199], v[108:111]
	v_mfma_f32_16x16x32_bf16 v[104:107], v[164:167], v[196:199], v[104:107]
	v_mfma_f32_16x16x32_bf16 v[92:95], v[148:151], v[208:211], v[92:95]
	v_mfma_f32_16x16x32_bf16 v[88:91], v[164:167], v[208:211], v[88:91]
	v_mfma_f32_16x16x32_bf16 v[76:79], v[148:151], v[216:219], v[76:79]
	v_mfma_f32_16x16x32_bf16 v[72:75], v[164:167], v[216:219], v[72:75]
	v_mfma_f32_16x16x32_bf16 v[124:127], v[160:163], v[192:195], v[124:127]
	v_mfma_f32_16x16x32_bf16 v[120:123], v[168:171], v[192:195], v[120:123]
	v_mfma_f32_16x16x32_bf16 v[108:111], v[160:163], v[200:203], v[108:111]
	v_mfma_f32_16x16x32_bf16 v[104:107], v[168:171], v[200:203], v[104:107]
	v_mfma_f32_16x16x32_bf16 v[92:95], v[160:163], v[212:215], v[92:95]
	v_mfma_f32_16x16x32_bf16 v[88:91], v[168:171], v[212:215], v[88:91]
	v_mfma_f32_16x16x32_bf16 v[76:79], v[160:163], v[220:223], v[76:79]
	v_mfma_f32_16x16x32_bf16 v[72:75], v[168:171], v[220:223], v[72:75]
	v_mfma_f32_16x16x32_bf16 v[116:119], v[172:175], v[188:191], v[116:119]
	v_mfma_f32_16x16x32_bf16 v[112:115], v[180:183], v[188:191], v[112:115]
	v_mfma_f32_16x16x32_bf16 v[100:103], v[172:175], v[196:199], v[100:103]
	v_mfma_f32_16x16x32_bf16 v[96:99], v[180:183], v[196:199], v[96:99]
	v_mfma_f32_16x16x32_bf16 v[84:87], v[172:175], v[208:211], v[84:87]
	v_mfma_f32_16x16x32_bf16 v[80:83], v[180:183], v[208:211], v[80:83]
	v_mfma_f32_16x16x32_bf16 v[68:71], v[172:175], v[216:219], v[68:71]
	v_mfma_f32_16x16x32_bf16 v[64:67], v[180:183], v[216:219], v[64:67]
	v_mfma_f32_16x16x32_bf16 v[116:119], v[176:179], v[192:195], v[116:119]
	v_mfma_f32_16x16x32_bf16 v[112:115], v[184:187], v[192:195], v[112:115]
	v_mfma_f32_16x16x32_bf16 v[100:103], v[176:179], v[200:203], v[100:103]
	v_mfma_f32_16x16x32_bf16 v[96:99], v[184:187], v[200:203], v[96:99]
	v_mfma_f32_16x16x32_bf16 v[84:87], v[176:179], v[212:215], v[84:87]
	v_mfma_f32_16x16x32_bf16 v[80:83], v[184:187], v[212:215], v[80:83]
	v_mfma_f32_16x16x32_bf16 v[68:71], v[176:179], v[220:223], v[68:71]
	v_mfma_f32_16x16x32_bf16 v[64:67], v[184:187], v[220:223], v[64:67]
	s_barrier
	s_setprio 0
	s_add_i32 s0, s0, s41
	s_add_u32 s100, s36, 0x80
	s_addc_u32 s101, s37, 0
	s_mov_b32 m0, s0
	ds_read_b128 v[188:191], v158 offset:49152
	global_load_lds_dwordx4 v132, s[100:101]
	s_add_i32 m0, s0, 0x2000
	ds_read_b128 v[192:195], v158 offset:50176
	global_load_lds_dwordx4 v136, s[100:101]
	s_add_u32 s36, s36, 0x100080
	s_addc_u32 s37, s37, 0
	s_add_i32 s0, s1, s41
	s_mov_b32 m0, s0
	ds_read_b128 v[196:199], v158 offset:51200
	global_load_lds_dwordx4 v132, s[36:37]
	s_add_i32 m0, s0, 0x2000
	ds_read_b128 v[200:203], v158 offset:52224
	global_load_lds_dwordx4 v136, s[36:37]
	s_add_u32 s100, s38, 0xfff00080
	s_addc_u32 s101, s39, -1
	s_mov_b32 m0, s46
	ds_read_b128 v[208:211], v158 offset:53248
	global_load_lds_dwordx4 v130, s[100:101]
	s_mov_b32 m0, s47
	ds_read_b128 v[212:215], v158 offset:54272
	global_load_lds_dwordx4 v134, s[100:101]
	ds_read_b128 v[216:219], v158 offset:55296
	ds_read_b128 v[220:223], v158 offset:56320
	s_waitcnt vmcnt(8) lgkmcnt(0)
	s_setprio 3
	s_barrier
	v_mfma_f32_16x16x32_bf16 v[60:63], v[148:151], v[188:191], v[60:63]
	v_mfma_f32_16x16x32_bf16 v[56:59], v[164:167], v[188:191], v[56:59]
	v_mfma_f32_16x16x32_bf16 v[44:47], v[148:151], v[196:199], v[44:47]
	v_mfma_f32_16x16x32_bf16 v[40:43], v[164:167], v[196:199], v[40:43]
	v_mfma_f32_16x16x32_bf16 v[28:31], v[148:151], v[208:211], v[28:31]
	v_mfma_f32_16x16x32_bf16 v[24:27], v[164:167], v[208:211], v[24:27]
	v_mfma_f32_16x16x32_bf16 v[12:15], v[148:151], v[216:219], v[12:15]
	v_mfma_f32_16x16x32_bf16 v[8:11], v[164:167], v[216:219], v[8:11]
	v_mfma_f32_16x16x32_bf16 v[60:63], v[160:163], v[192:195], v[60:63]
	v_mfma_f32_16x16x32_bf16 v[56:59], v[168:171], v[192:195], v[56:59]
	v_mfma_f32_16x16x32_bf16 v[44:47], v[160:163], v[200:203], v[44:47]
	v_mfma_f32_16x16x32_bf16 v[40:43], v[168:171], v[200:203], v[40:43]
	v_mfma_f32_16x16x32_bf16 v[28:31], v[160:163], v[212:215], v[28:31]
	v_mfma_f32_16x16x32_bf16 v[24:27], v[168:171], v[212:215], v[24:27]
	v_mfma_f32_16x16x32_bf16 v[12:15], v[160:163], v[220:223], v[12:15]
	v_mfma_f32_16x16x32_bf16 v[8:11], v[168:171], v[220:223], v[8:11]
	s_add_u32 s34, s34, 0x100
	s_addc_u32 s35, s35, 0
	s_add_i32 s60, s60, 2
	s_add_u32 s58, s58, 0x100
	s_addc_u32 s59, s59, 0
	v_mfma_f32_16x16x32_bf16 v[52:55], v[172:175], v[188:191], v[52:55]
	v_mfma_f32_16x16x32_bf16 v[48:51], v[180:183], v[188:191], v[48:51]
	v_mfma_f32_16x16x32_bf16 v[36:39], v[172:175], v[196:199], v[36:39]
	v_mfma_f32_16x16x32_bf16 v[32:35], v[180:183], v[196:199], v[32:35]
	v_mfma_f32_16x16x32_bf16 v[20:23], v[172:175], v[208:211], v[20:23]
	v_mfma_f32_16x16x32_bf16 v[16:19], v[180:183], v[208:211], v[16:19]
	v_mfma_f32_16x16x32_bf16 v[4:7], v[172:175], v[216:219], v[4:7]
	v_mfma_f32_16x16x32_bf16 v[0:3], v[180:183], v[216:219], v[0:3]
	v_mfma_f32_16x16x32_bf16 v[52:55], v[176:179], v[192:195], v[52:55]
	v_mfma_f32_16x16x32_bf16 v[48:51], v[184:187], v[192:195], v[48:51]
	v_mfma_f32_16x16x32_bf16 v[36:39], v[176:179], v[200:203], v[36:39]
	v_mfma_f32_16x16x32_bf16 v[32:35], v[184:187], v[200:203], v[32:35]
	v_mfma_f32_16x16x32_bf16 v[20:23], v[176:179], v[212:215], v[20:23]
	v_mfma_f32_16x16x32_bf16 v[16:19], v[184:187], v[212:215], v[16:19]
	v_mfma_f32_16x16x32_bf16 v[4:7], v[176:179], v[220:223], v[4:7]
	v_mfma_f32_16x16x32_bf16 v[0:3], v[184:187], v[220:223], v[0:3]
	s_barrier
	s_setprio 0
	s_cmp_gt_u32 s60, 61
	s_cbranch_scc0 .LBB0_134
	s_and_b64 vcc, exec, s[10:11]
	s_cbranch_vccz .LBB0_137
	s_barrier

.LBB0_677:
	ds_read_b128 v[156:159], v152
	ds_read_b128 v[160:163], v152 offset:1024
	ds_read_b128 v[164:167], v152 offset:2048
	ds_read_b128 v[168:171], v152 offset:3072
	ds_read_b128 v[172:175], v153
	ds_read_b128 v[176:179], v153 offset:1024
	ds_read_b128 v[180:183], v153 offset:2048
	ds_read_b128 v[184:187], v153 offset:3072
	s_add_u32 s0, s36, 0xfff00080
	s_addc_u32 s1, s37, -1
	s_cmp_eq_u32 s61, 60
	s_cselect_b32 s41, s56, s1
	s_cselect_b32 s40, s57, s0
	s_cselect_b32 s39, s15, s60
	s_cselect_b32 s38, s58, s59
	s_add_i32 m0, s31, 0xc000
	ds_read_b128 v[188:191], v154
	ds_read_b128 v[192:195], v154 offset:1024
	ds_read_b128 v[196:199], v154 offset:2048
	ds_read_b128 v[200:203], v154 offset:3072
	ds_read_b128 v[204:207], v154 offset:4096
	ds_read_b128 v[208:211], v154 offset:5120
	ds_read_b128 v[212:215], v154 offset:6144
	global_load_lds_dwordx4 v138, s[36:37]
	s_add_i32 m0, s31, 0xe000
	ds_read_b128 v[216:219], v154 offset:7168
	global_load_lds_dwordx4 v140, s[36:37]
	s_waitcnt vmcnt(8) lgkmcnt(0)
	s_setprio 3
	s_barrier
	v_mfma_f32_16x16x32_bf16 v[124:127], v[156:159], v[188:191], v[124:127]
	v_mfma_f32_16x16x32_bf16 v[120:123], v[164:167], v[188:191], v[120:123]
	v_mfma_f32_16x16x32_bf16 v[108:111], v[156:159], v[196:199], v[108:111]
	v_mfma_f32_16x16x32_bf16 v[104:107], v[164:167], v[196:199], v[104:107]
	v_mfma_f32_16x16x32_bf16 v[92:95], v[156:159], v[204:207], v[92:95]
	v_mfma_f32_16x16x32_bf16 v[88:91], v[164:167], v[204:207], v[88:91]
	v_mfma_f32_16x16x32_bf16 v[76:79], v[156:159], v[212:215], v[76:79]
	v_mfma_f32_16x16x32_bf16 v[72:75], v[164:167], v[212:215], v[72:75]
	v_mfma_f32_16x16x32_bf16 v[124:127], v[160:163], v[192:195], v[124:127]
	v_mfma_f32_16x16x32_bf16 v[120:123], v[168:171], v[192:195], v[120:123]
	v_mfma_f32_16x16x32_bf16 v[108:111], v[160:163], v[200:203], v[108:111]
	v_mfma_f32_16x16x32_bf16 v[104:107], v[168:171], v[200:203], v[104:107]
	v_mfma_f32_16x16x32_bf16 v[92:95], v[160:163], v[208:211], v[92:95]
	v_mfma_f32_16x16x32_bf16 v[88:91], v[168:171], v[208:211], v[88:91]
	v_mfma_f32_16x16x32_bf16 v[76:79], v[160:163], v[216:219], v[76:79]
	v_mfma_f32_16x16x32_bf16 v[72:75], v[168:171], v[216:219], v[72:75]
	v_mfma_f32_16x16x32_bf16 v[116:119], v[172:175], v[188:191], v[116:119]
	v_mfma_f32_16x16x32_bf16 v[112:115], v[180:183], v[188:191], v[112:115]
	v_mfma_f32_16x16x32_bf16 v[100:103], v[172:175], v[196:199], v[100:103]
	v_mfma_f32_16x16x32_bf16 v[96:99], v[180:183], v[196:199], v[96:99]
	v_mfma_f32_16x16x32_bf16 v[84:87], v[172:175], v[204:207], v[84:87]
	v_mfma_f32_16x16x32_bf16 v[80:83], v[180:183], v[204:207], v[80:83]
	v_mfma_f32_16x16x32_bf16 v[68:71], v[172:175], v[212:215], v[68:71]
	v_mfma_f32_16x16x32_bf16 v[64:67], v[180:183], v[212:215], v[64:67]
	v_mfma_f32_16x16x32_bf16 v[116:119], v[176:179], v[192:195], v[116:119]
	v_mfma_f32_16x16x32_bf16 v[112:115], v[184:187], v[192:195], v[112:115]
	v_mfma_f32_16x16x32_bf16 v[100:103], v[176:179], v[200:203], v[100:103]
	v_mfma_f32_16x16x32_bf16 v[96:99], v[184:187], v[200:203], v[96:99]
	v_mfma_f32_16x16x32_bf16 v[84:87], v[176:179], v[208:211], v[84:87]
	v_mfma_f32_16x16x32_bf16 v[80:83], v[184:187], v[208:211], v[80:83]
	v_mfma_f32_16x16x32_bf16 v[68:71], v[176:179], v[216:219], v[68:71]
	v_mfma_f32_16x16x32_bf16 v[64:67], v[184:187], v[216:219], v[64:67]
	s_barrier
	s_setprio 0
	s_add_i32 s0, s51, s43
	s_mov_b32 m0, s0
	ds_read_b128 v[188:191], v154 offset:16384
	ds_read_b128 v[192:195], v154 offset:17408
	ds_read_b128 v[196:199], v154 offset:18432
	ds_read_b128 v[200:203], v154 offset:19456
	ds_read_b128 v[204:207], v154 offset:20480
	global_load_lds_dwordx4 v130, s[38:39]
	s_add_i32 m0, s0, 0x2000
	s_add_u32 s0, s38, 0x100000
	s_addc_u32 s1, s39, 0
	s_add_i32 s62, s52, s43
	global_load_lds_dwordx4 v134, s[38:39]
	s_mov_b32 m0, s62
	s_nop 0
	global_load_lds_dwordx4 v130, s[0:1]
	s_add_i32 m0, s62, 0x2000
	ds_read_b128 v[216:219], v154 offset:23552
	global_load_lds_dwordx4 v134, s[0:1]
	s_mov_b32 m0, s31
	ds_read_b128 v[212:215], v154 offset:22528
	global_load_lds_dwordx4 v128, s[40:41]
	s_mov_b32 m0, s35
	ds_read_b128 v[208:211], v154 offset:21504
	global_load_lds_dwordx4 v132, s[40:41]
	s_waitcnt vmcnt(8) lgkmcnt(0)
	s_setprio 3
	s_barrier
	v_mfma_f32_16x16x32_bf16 v[60:63], v[156:159], v[188:191], v[60:63]
	v_mfma_f32_16x16x32_bf16 v[56:59], v[164:167], v[188:191], v[56:59]
	v_mfma_f32_16x16x32_bf16 v[44:47], v[156:159], v[196:199], v[44:47]
	v_mfma_f32_16x16x32_bf16 v[40:43], v[164:167], v[196:199], v[40:43]
	v_mfma_f32_16x16x32_bf16 v[28:31], v[156:159], v[204:207], v[28:31]
	v_mfma_f32_16x16x32_bf16 v[24:27], v[164:167], v[204:207], v[24:27]
	v_mfma_f32_16x16x32_bf16 v[12:15], v[156:159], v[212:215], v[12:15]
	v_mfma_f32_16x16x32_bf16 v[8:11], v[164:167], v[212:215], v[8:11]
	v_mfma_f32_16x16x32_bf16 v[60:63], v[160:163], v[192:195], v[60:63]
	v_mfma_f32_16x16x32_bf16 v[56:59], v[168:171], v[192:195], v[56:59]
	v_mfma_f32_16x16x32_bf16 v[44:47], v[160:163], v[200:203], v[44:47]
	v_mfma_f32_16x16x32_bf16 v[40:43], v[168:171], v[200:203], v[40:43]
	v_mfma_f32_16x16x32_bf16 v[28:31], v[160:163], v[208:211], v[28:31]
	v_mfma_f32_16x16x32_bf16 v[24:27], v[168:171], v[208:211], v[24:27]
	v_mfma_f32_16x16x32_bf16 v[12:15], v[160:163], v[216:219], v[12:15]
	v_mfma_f32_16x16x32_bf16 v[8:11], v[168:171], v[216:219], v[8:11]
	v_mfma_f32_16x16x32_bf16 v[52:55], v[172:175], v[188:191], v[52:55]
	v_mfma_f32_16x16x32_bf16 v[48:51], v[180:183], v[188:191], v[48:51]
	v_mfma_f32_16x16x32_bf16 v[36:39], v[172:175], v[196:199], v[36:39]
	v_mfma_f32_16x16x32_bf16 v[32:35], v[180:183], v[196:199], v[32:35]
	v_mfma_f32_16x16x32_bf16 v[20:23], v[172:175], v[204:207], v[20:23]
	v_mfma_f32_16x16x32_bf16 v[16:19], v[180:183], v[204:207], v[16:19]
	v_mfma_f32_16x16x32_bf16 v[4:7], v[172:175], v[212:215], v[4:7]
	v_mfma_f32_16x16x32_bf16 v[0:3], v[180:183], v[212:215], v[0:3]
	v_mfma_f32_16x16x32_bf16 v[52:55], v[176:179], v[192:195], v[52:55]
	v_mfma_f32_16x16x32_bf16 v[48:51], v[184:187], v[192:195], v[48:51]
	v_mfma_f32_16x16x32_bf16 v[36:39], v[176:179], v[200:203], v[36:39]
	v_mfma_f32_16x16x32_bf16 v[32:35], v[184:187], v[200:203], v[32:35]
	v_mfma_f32_16x16x32_bf16 v[20:23], v[176:179], v[208:211], v[20:23]
	v_mfma_f32_16x16x32_bf16 v[16:19], v[184:187], v[208:211], v[16:19]
	v_mfma_f32_16x16x32_bf16 v[4:7], v[176:179], v[216:219], v[4:7]
	v_mfma_f32_16x16x32_bf16 v[0:3], v[184:187], v[216:219], v[0:3]
	s_barrier
	s_setprio 0
	s_add_i32 s62, 0, 0x18000
	s_add_i32 s63, 0, 0x1c000
	ds_read_b128 v[156:159], v226
	ds_read_b128 v[160:163], v226 offset:1024
	ds_read_b128 v[164:167], v226 offset:2048
	ds_read_b128 v[168:171], v226 offset:3072
	ds_read_b128 v[172:175], v227
	ds_read_b128 v[176:179], v227 offset:1024
	ds_read_b128 v[180:183], v227 offset:2048
	ds_read_b128 v[184:187], v227 offset:3072
	s_add_u32 s0, s40, 0x100000
	s_addc_u32 s1, s41, 0
	s_mov_b32 m0, s44
	ds_read_b128 v[188:191], v154 offset:32768
	ds_read_b128 v[192:195], v154 offset:33792
	ds_read_b128 v[196:199], v154 offset:34816
	ds_read_b128 v[200:203], v154 offset:35840
	ds_read_b128 v[204:207], v154 offset:36864
	ds_read_b128 v[208:211], v154 offset:37888
	ds_read_b128 v[212:215], v154 offset:38912
	global_load_lds_dwordx4 v128, s[0:1]
	s_mov_b32 m0, s45
	ds_read_b128 v[216:219], v154 offset:39936
	global_load_lds_dwordx4 v132, s[0:1]
	s_waitcnt vmcnt(8) lgkmcnt(0)
	s_setprio 3
	s_barrier
	v_mfma_f32_16x16x32_bf16 v[124:127], v[156:159], v[188:191], v[124:127]
	v_mfma_f32_16x16x32_bf16 v[120:123], v[164:167], v[188:191], v[120:123]
	v_mfma_f32_16x16x32_bf16 v[108:111], v[156:159], v[196:199], v[108:111]
	v_mfma_f32_16x16x32_bf16 v[104:107], v[164:167], v[196:199], v[104:107]
	v_mfma_f32_16x16x32_bf16 v[92:95], v[156:159], v[204:207], v[92:95]
	v_mfma_f32_16x16x32_bf16 v[88:91], v[164:167], v[204:207], v[88:91]
	v_mfma_f32_16x16x32_bf16 v[76:79], v[156:159], v[212:215], v[76:79]
	v_mfma_f32_16x16x32_bf16 v[72:75], v[164:167], v[212:215], v[72:75]
	v_mfma_f32_16x16x32_bf16 v[124:127], v[160:163], v[192:195], v[124:127]
	v_mfma_f32_16x16x32_bf16 v[120:123], v[168:171], v[192:195], v[120:123]
	v_mfma_f32_16x16x32_bf16 v[108:111], v[160:163], v[200:203], v[108:111]
	v_mfma_f32_16x16x32_bf16 v[104:107], v[168:171], v[200:203], v[104:107]
	v_mfma_f32_16x16x32_bf16 v[92:95], v[160:163], v[208:211], v[92:95]
	v_mfma_f32_16x16x32_bf16 v[88:91], v[168:171], v[208:211], v[88:91]
	v_mfma_f32_16x16x32_bf16 v[76:79], v[160:163], v[216:219], v[76:79]
	v_mfma_f32_16x16x32_bf16 v[72:75], v[168:171], v[216:219], v[72:75]
	v_mfma_f32_16x16x32_bf16 v[116:119], v[172:175], v[188:191], v[116:119]
	v_mfma_f32_16x16x32_bf16 v[112:115], v[180:183], v[188:191], v[112:115]
	v_mfma_f32_16x16x32_bf16 v[100:103], v[172:175], v[196:199], v[100:103]
	v_mfma_f32_16x16x32_bf16 v[96:99], v[180:183], v[196:199], v[96:99]
	v_mfma_f32_16x16x32_bf16 v[84:87], v[172:175], v[204:207], v[84:87]
	v_mfma_f32_16x16x32_bf16 v[80:83], v[180:183], v[204:207], v[80:83]
	v_mfma_f32_16x16x32_bf16 v[68:71], v[172:175], v[212:215], v[68:71]
	v_mfma_f32_16x16x32_bf16 v[64:67], v[180:183], v[212:215], v[64:67]
	v_mfma_f32_16x16x32_bf16 v[116:119], v[176:179], v[192:195], v[116:119]
	v_mfma_f32_16x16x32_bf16 v[112:115], v[184:187], v[192:195], v[112:115]
	v_mfma_f32_16x16x32_bf16 v[100:103], v[176:179], v[200:203], v[100:103]
	v_mfma_f32_16x16x32_bf16 v[96:99], v[184:187], v[200:203], v[96:99]
	v_mfma_f32_16x16x32_bf16 v[84:87], v[176:179], v[208:211], v[84:87]
	v_mfma_f32_16x16x32_bf16 v[80:83], v[184:187], v[208:211], v[80:83]
	v_mfma_f32_16x16x32_bf16 v[68:71], v[176:179], v[216:219], v[68:71]
	v_mfma_f32_16x16x32_bf16 v[64:67], v[184:187], v[216:219], v[64:67]
	s_barrier
	s_setprio 0
	s_add_i32 s0, s62, s43
	s_add_u32 s100, s38, 0x80
	s_addc_u32 s101, s39, 0
	s_mov_b32 m0, s0
	ds_read_b128 v[188:191], v154 offset:49152
	ds_read_b128 v[192:195], v154 offset:50176
	ds_read_b128 v[196:199], v154 offset:51200
	ds_read_b128 v[200:203], v154 offset:52224
	global_load_lds_dwordx4 v130, s[100:101]
	s_add_i32 m0, s0, 0x2000
	s_add_u32 s0, s38, 0x100080
	s_addc_u32 s1, s39, 0
	s_add_i32 s38, s63, s43
	global_load_lds_dwordx4 v134, s[100:101]
	s_mov_b32 m0, s38
	ds_read_b128 v[216:219], v154 offset:56320
	global_load_lds_dwordx4 v130, s[0:1]
	s_add_i32 m0, s38, 0x2000
	ds_read_b128 v[212:215], v154 offset:55296
	global_load_lds_dwordx4 v134, s[0:1]
	s_add_u32 s100, s40, 0x80
	s_addc_u32 s101, s41, 0
	s_mov_b32 m0, s46
	ds_read_b128 v[208:211], v154 offset:54272
	global_load_lds_dwordx4 v128, s[100:101]
	s_mov_b32 m0, s47
	ds_read_b128 v[204:207], v154 offset:53248
	global_load_lds_dwordx4 v132, s[100:101]
	s_waitcnt vmcnt(8) lgkmcnt(0)
	s_setprio 3
	s_barrier
	v_mfma_f32_16x16x32_bf16 v[60:63], v[156:159], v[188:191], v[60:63]
	v_mfma_f32_16x16x32_bf16 v[56:59], v[164:167], v[188:191], v[56:59]
	v_mfma_f32_16x16x32_bf16 v[44:47], v[156:159], v[196:199], v[44:47]
	v_mfma_f32_16x16x32_bf16 v[40:43], v[164:167], v[196:199], v[40:43]
	v_mfma_f32_16x16x32_bf16 v[28:31], v[156:159], v[204:207], v[28:31]
	v_mfma_f32_16x16x32_bf16 v[24:27], v[164:167], v[204:207], v[24:27]
	v_mfma_f32_16x16x32_bf16 v[12:15], v[156:159], v[212:215], v[12:15]
	v_mfma_f32_16x16x32_bf16 v[8:11], v[164:167], v[212:215], v[8:11]
	v_mfma_f32_16x16x32_bf16 v[60:63], v[160:163], v[192:195], v[60:63]
	v_mfma_f32_16x16x32_bf16 v[56:59], v[168:171], v[192:195], v[56:59]
	v_mfma_f32_16x16x32_bf16 v[44:47], v[160:163], v[200:203], v[44:47]
	v_mfma_f32_16x16x32_bf16 v[40:43], v[168:171], v[200:203], v[40:43]
	v_mfma_f32_16x16x32_bf16 v[28:31], v[160:163], v[208:211], v[28:31]
	v_mfma_f32_16x16x32_bf16 v[24:27], v[168:171], v[208:211], v[24:27]
	v_mfma_f32_16x16x32_bf16 v[12:15], v[160:163], v[216:219], v[12:15]
	v_mfma_f32_16x16x32_bf16 v[8:11], v[168:171], v[216:219], v[8:11]
	s_add_u32 s36, s36, 0x100
	s_addc_u32 s37, s37, 0
	s_add_i32 s61, s61, 2
	s_add_u32 s59, s59, 0x100
	s_addc_u32 s60, s60, 0
	v_mfma_f32_16x16x32_bf16 v[52:55], v[172:175], v[188:191], v[52:55]
	v_mfma_f32_16x16x32_bf16 v[48:51], v[180:183], v[188:191], v[48:51]
	v_mfma_f32_16x16x32_bf16 v[36:39], v[172:175], v[196:199], v[36:39]
	v_mfma_f32_16x16x32_bf16 v[32:35], v[180:183], v[196:199], v[32:35]
	v_mfma_f32_16x16x32_bf16 v[20:23], v[172:175], v[204:207], v[20:23]
	v_mfma_f32_16x16x32_bf16 v[16:19], v[180:183], v[204:207], v[16:19]
	v_mfma_f32_16x16x32_bf16 v[4:7], v[172:175], v[212:215], v[4:7]
	v_mfma_f32_16x16x32_bf16 v[0:3], v[180:183], v[212:215], v[0:3]
	v_mfma_f32_16x16x32_bf16 v[52:55], v[176:179], v[192:195], v[52:55]
	v_mfma_f32_16x16x32_bf16 v[48:51], v[184:187], v[192:195], v[48:51]
	v_mfma_f32_16x16x32_bf16 v[36:39], v[176:179], v[200:203], v[36:39]
	v_mfma_f32_16x16x32_bf16 v[32:35], v[184:187], v[200:203], v[32:35]
	v_mfma_f32_16x16x32_bf16 v[20:23], v[176:179], v[208:211], v[20:23]
	v_mfma_f32_16x16x32_bf16 v[16:19], v[184:187], v[208:211], v[16:19]
	v_mfma_f32_16x16x32_bf16 v[4:7], v[176:179], v[216:219], v[4:7]
	v_mfma_f32_16x16x32_bf16 v[0:3], v[184:187], v[216:219], v[0:3]
	s_barrier
	s_setprio 0
	s_cmp_gt_u32 s61, 61
	s_cbranch_scc0 .LBB0_677
	s_and_b64 vcc, exec, s[12:13]
	s_cbranch_vccz .LBB0_680
	s_barrier

.LBB0_1637:
	ds_read_b128 v[152:155], v149
	ds_read_b128 v[156:159], v149 offset:1024
	ds_read_b128 v[160:163], v149 offset:2048
	ds_read_b128 v[164:167], v149 offset:3072
	ds_read_b128 v[168:171], v150
	ds_read_b128 v[172:175], v150 offset:1024
	ds_read_b128 v[176:179], v150 offset:2048
	ds_read_b128 v[180:183], v150 offset:3072
	s_add_u32 s0, s42, 0xfff00080
	s_addc_u32 s1, s43, -1
	s_cmp_eq_u32 s68, 60
	s_cselect_b32 s47, s35, s1
	s_cselect_b32 s46, s64, s0
	s_cselect_b32 s45, s31, s67
	s_cselect_b32 s44, s65, s66
	s_add_i32 m0, s41, 0xc000
	ds_read_b128 v[184:187], v151
	ds_read_b128 v[188:191], v151 offset:1024
	ds_read_b128 v[192:195], v151 offset:2048
	ds_read_b128 v[196:199], v151 offset:3072
	ds_read_b128 v[200:203], v151 offset:4096
	ds_read_b128 v[210:213], v151 offset:5120
	ds_read_b128 v[214:217], v151 offset:6144
	global_load_lds_dwordx4 v136, s[42:43]
	s_add_i32 m0, s41, 0xe000
	ds_read_b128 v[218:221], v151 offset:7168
	global_load_lds_dwordx4 v138, s[42:43]
	s_waitcnt vmcnt(8) lgkmcnt(0)
	s_setprio 3
	s_barrier
	v_mfma_f32_16x16x32_bf16 v[124:127], v[152:155], v[184:187], v[124:127]
	v_mfma_f32_16x16x32_bf16 v[120:123], v[160:163], v[184:187], v[120:123]
	v_mfma_f32_16x16x32_bf16 v[116:119], v[152:155], v[192:195], v[116:119]
	v_mfma_f32_16x16x32_bf16 v[108:111], v[160:163], v[192:195], v[108:111]
	v_mfma_f32_16x16x32_bf16 v[100:103], v[152:155], v[200:203], v[100:103]
	v_mfma_f32_16x16x32_bf16 v[92:95], v[160:163], v[200:203], v[92:95]
	v_mfma_f32_16x16x32_bf16 v[84:87], v[152:155], v[214:217], v[84:87]
	v_mfma_f32_16x16x32_bf16 v[76:79], v[160:163], v[214:217], v[76:79]
	v_mfma_f32_16x16x32_bf16 v[124:127], v[156:159], v[188:191], v[124:127]
	v_mfma_f32_16x16x32_bf16 v[120:123], v[164:167], v[188:191], v[120:123]
	v_mfma_f32_16x16x32_bf16 v[116:119], v[156:159], v[196:199], v[116:119]
	v_mfma_f32_16x16x32_bf16 v[108:111], v[164:167], v[196:199], v[108:111]
	v_mfma_f32_16x16x32_bf16 v[100:103], v[156:159], v[210:213], v[100:103]
	v_mfma_f32_16x16x32_bf16 v[92:95], v[164:167], v[210:213], v[92:95]
	v_mfma_f32_16x16x32_bf16 v[84:87], v[156:159], v[218:221], v[84:87]
	v_mfma_f32_16x16x32_bf16 v[76:79], v[164:167], v[218:221], v[76:79]
	v_mfma_f32_16x16x32_bf16 v[112:115], v[168:171], v[184:187], v[112:115]
	v_mfma_f32_16x16x32_bf16 v[104:107], v[176:179], v[184:187], v[104:107]
	v_mfma_f32_16x16x32_bf16 v[96:99], v[168:171], v[192:195], v[96:99]
	v_mfma_f32_16x16x32_bf16 v[88:91], v[176:179], v[192:195], v[88:91]
	v_mfma_f32_16x16x32_bf16 v[80:83], v[168:171], v[200:203], v[80:83]
	v_mfma_f32_16x16x32_bf16 v[72:75], v[176:179], v[200:203], v[72:75]
	v_mfma_f32_16x16x32_bf16 v[68:71], v[168:171], v[214:217], v[68:71]
	v_mfma_f32_16x16x32_bf16 v[64:67], v[176:179], v[214:217], v[64:67]
	v_mfma_f32_16x16x32_bf16 v[112:115], v[172:175], v[188:191], v[112:115]
	v_mfma_f32_16x16x32_bf16 v[104:107], v[180:183], v[188:191], v[104:107]
	v_mfma_f32_16x16x32_bf16 v[96:99], v[172:175], v[196:199], v[96:99]
	v_mfma_f32_16x16x32_bf16 v[88:91], v[180:183], v[196:199], v[88:91]
	v_mfma_f32_16x16x32_bf16 v[80:83], v[172:175], v[210:213], v[80:83]
	v_mfma_f32_16x16x32_bf16 v[72:75], v[180:183], v[210:213], v[72:75]
	v_mfma_f32_16x16x32_bf16 v[68:71], v[172:175], v[218:221], v[68:71]
	v_mfma_f32_16x16x32_bf16 v[64:67], v[180:183], v[218:221], v[64:67]
	s_barrier
	s_setprio 0
	s_add_i32 s0, s57, s49
	s_mov_b32 m0, s0
	ds_read_b128 v[184:187], v151 offset:16384
	ds_read_b128 v[188:191], v151 offset:17408
	ds_read_b128 v[192:195], v151 offset:18432
	ds_read_b128 v[196:199], v151 offset:19456
	ds_read_b128 v[200:203], v151 offset:20480
	global_load_lds_dwordx4 v130, s[44:45]
	s_add_i32 m0, s0, 0x2000
	s_add_u32 s0, s44, 0x100000
	s_addc_u32 s1, s45, 0
	s_add_i32 s69, s58, s49
	global_load_lds_dwordx4 v134, s[44:45]
	s_mov_b32 m0, s69
	s_nop 0
	global_load_lds_dwordx4 v130, s[0:1]
	s_add_i32 m0, s69, 0x2000
	ds_read_b128 v[218:221], v151 offset:23552
	global_load_lds_dwordx4 v134, s[0:1]
	s_mov_b32 m0, s41
	ds_read_b128 v[214:217], v151 offset:22528
	global_load_lds_dwordx4 v128, s[46:47]
	s_mov_b32 m0, s50
	ds_read_b128 v[210:213], v151 offset:21504
	global_load_lds_dwordx4 v132, s[46:47]
	s_waitcnt vmcnt(8) lgkmcnt(0)
	s_setprio 3
	s_barrier
	v_mfma_f32_16x16x32_bf16 v[60:63], v[152:155], v[184:187], v[60:63]
	v_mfma_f32_16x16x32_bf16 v[56:59], v[160:163], v[184:187], v[56:59]
	v_mfma_f32_16x16x32_bf16 v[52:55], v[152:155], v[192:195], v[52:55]
	v_mfma_f32_16x16x32_bf16 v[44:47], v[160:163], v[192:195], v[44:47]
	v_mfma_f32_16x16x32_bf16 v[36:39], v[152:155], v[200:203], v[36:39]
	v_mfma_f32_16x16x32_bf16 v[28:31], v[160:163], v[200:203], v[28:31]
	v_mfma_f32_16x16x32_bf16 v[20:23], v[152:155], v[214:217], v[20:23]
	v_mfma_f32_16x16x32_bf16 v[12:15], v[160:163], v[214:217], v[12:15]
	v_mfma_f32_16x16x32_bf16 v[60:63], v[156:159], v[188:191], v[60:63]
	v_mfma_f32_16x16x32_bf16 v[56:59], v[164:167], v[188:191], v[56:59]
	v_mfma_f32_16x16x32_bf16 v[52:55], v[156:159], v[196:199], v[52:55]
	v_mfma_f32_16x16x32_bf16 v[44:47], v[164:167], v[196:199], v[44:47]
	v_mfma_f32_16x16x32_bf16 v[36:39], v[156:159], v[210:213], v[36:39]
	v_mfma_f32_16x16x32_bf16 v[28:31], v[164:167], v[210:213], v[28:31]
	v_mfma_f32_16x16x32_bf16 v[20:23], v[156:159], v[218:221], v[20:23]
	v_mfma_f32_16x16x32_bf16 v[12:15], v[164:167], v[218:221], v[12:15]
	v_mfma_f32_16x16x32_bf16 v[48:51], v[168:171], v[184:187], v[48:51]
	v_mfma_f32_16x16x32_bf16 v[40:43], v[176:179], v[184:187], v[40:43]
	v_mfma_f32_16x16x32_bf16 v[32:35], v[168:171], v[192:195], v[32:35]
	v_mfma_f32_16x16x32_bf16 v[24:27], v[176:179], v[192:195], v[24:27]
	v_mfma_f32_16x16x32_bf16 v[16:19], v[168:171], v[200:203], v[16:19]
	v_mfma_f32_16x16x32_bf16 v[8:11], v[176:179], v[200:203], v[8:11]
	v_mfma_f32_16x16x32_bf16 v[4:7], v[168:171], v[214:217], v[4:7]
	v_mfma_f32_16x16x32_bf16 v[0:3], v[176:179], v[214:217], v[0:3]
	v_mfma_f32_16x16x32_bf16 v[48:51], v[172:175], v[188:191], v[48:51]
	v_mfma_f32_16x16x32_bf16 v[40:43], v[180:183], v[188:191], v[40:43]
	v_mfma_f32_16x16x32_bf16 v[32:35], v[172:175], v[196:199], v[32:35]
	v_mfma_f32_16x16x32_bf16 v[24:27], v[180:183], v[196:199], v[24:27]
	v_mfma_f32_16x16x32_bf16 v[16:19], v[172:175], v[210:213], v[16:19]
	v_mfma_f32_16x16x32_bf16 v[8:11], v[180:183], v[210:213], v[8:11]
	v_mfma_f32_16x16x32_bf16 v[4:7], v[172:175], v[218:221], v[4:7]
	v_mfma_f32_16x16x32_bf16 v[0:3], v[180:183], v[218:221], v[0:3]
	s_barrier
	s_setprio 0
	s_add_i32 s69, 0, 0x18000
	s_add_i32 s70, 0, 0x1c000
	ds_read_b128 v[152:155], v228
	ds_read_b128 v[156:159], v228 offset:1024
	ds_read_b128 v[160:163], v228 offset:2048
	ds_read_b128 v[164:167], v228 offset:3072
	ds_read_b128 v[168:171], v229
	ds_read_b128 v[172:175], v229 offset:1024
	ds_read_b128 v[176:179], v229 offset:2048
	ds_read_b128 v[180:183], v229 offset:3072
	s_add_u32 s0, s46, 0x100000
	s_addc_u32 s1, s47, 0
	s_mov_b32 m0, s51
	ds_read_b128 v[184:187], v151 offset:32768
	ds_read_b128 v[188:191], v151 offset:33792
	ds_read_b128 v[192:195], v151 offset:34816
	ds_read_b128 v[196:199], v151 offset:35840
	ds_read_b128 v[200:203], v151 offset:36864
	ds_read_b128 v[210:213], v151 offset:37888
	ds_read_b128 v[214:217], v151 offset:38912
	global_load_lds_dwordx4 v128, s[0:1]
	s_mov_b32 m0, s52
	ds_read_b128 v[218:221], v151 offset:39936
	global_load_lds_dwordx4 v132, s[0:1]
	s_waitcnt vmcnt(8) lgkmcnt(0)
	s_setprio 3
	s_barrier
	v_mfma_f32_16x16x32_bf16 v[124:127], v[152:155], v[184:187], v[124:127]
	v_mfma_f32_16x16x32_bf16 v[120:123], v[160:163], v[184:187], v[120:123]
	v_mfma_f32_16x16x32_bf16 v[116:119], v[152:155], v[192:195], v[116:119]
	v_mfma_f32_16x16x32_bf16 v[108:111], v[160:163], v[192:195], v[108:111]
	v_mfma_f32_16x16x32_bf16 v[100:103], v[152:155], v[200:203], v[100:103]
	v_mfma_f32_16x16x32_bf16 v[92:95], v[160:163], v[200:203], v[92:95]
	v_mfma_f32_16x16x32_bf16 v[84:87], v[152:155], v[214:217], v[84:87]
	v_mfma_f32_16x16x32_bf16 v[76:79], v[160:163], v[214:217], v[76:79]
	v_mfma_f32_16x16x32_bf16 v[124:127], v[156:159], v[188:191], v[124:127]
	v_mfma_f32_16x16x32_bf16 v[120:123], v[164:167], v[188:191], v[120:123]
	v_mfma_f32_16x16x32_bf16 v[116:119], v[156:159], v[196:199], v[116:119]
	v_mfma_f32_16x16x32_bf16 v[108:111], v[164:167], v[196:199], v[108:111]
	v_mfma_f32_16x16x32_bf16 v[100:103], v[156:159], v[210:213], v[100:103]
	v_mfma_f32_16x16x32_bf16 v[92:95], v[164:167], v[210:213], v[92:95]
	v_mfma_f32_16x16x32_bf16 v[84:87], v[156:159], v[218:221], v[84:87]
	v_mfma_f32_16x16x32_bf16 v[76:79], v[164:167], v[218:221], v[76:79]
	v_mfma_f32_16x16x32_bf16 v[112:115], v[168:171], v[184:187], v[112:115]
	v_mfma_f32_16x16x32_bf16 v[104:107], v[176:179], v[184:187], v[104:107]
	v_mfma_f32_16x16x32_bf16 v[96:99], v[168:171], v[192:195], v[96:99]
	v_mfma_f32_16x16x32_bf16 v[88:91], v[176:179], v[192:195], v[88:91]
	v_mfma_f32_16x16x32_bf16 v[80:83], v[168:171], v[200:203], v[80:83]
	v_mfma_f32_16x16x32_bf16 v[72:75], v[176:179], v[200:203], v[72:75]
	v_mfma_f32_16x16x32_bf16 v[68:71], v[168:171], v[214:217], v[68:71]
	v_mfma_f32_16x16x32_bf16 v[64:67], v[176:179], v[214:217], v[64:67]
	v_mfma_f32_16x16x32_bf16 v[112:115], v[172:175], v[188:191], v[112:115]
	v_mfma_f32_16x16x32_bf16 v[104:107], v[180:183], v[188:191], v[104:107]
	v_mfma_f32_16x16x32_bf16 v[96:99], v[172:175], v[196:199], v[96:99]
	v_mfma_f32_16x16x32_bf16 v[88:91], v[180:183], v[196:199], v[88:91]
	v_mfma_f32_16x16x32_bf16 v[80:83], v[172:175], v[210:213], v[80:83]
	v_mfma_f32_16x16x32_bf16 v[72:75], v[180:183], v[210:213], v[72:75]
	v_mfma_f32_16x16x32_bf16 v[68:71], v[172:175], v[218:221], v[68:71]
	v_mfma_f32_16x16x32_bf16 v[64:67], v[180:183], v[218:221], v[64:67]
	s_barrier
	s_setprio 0
	s_add_i32 s0, s69, s49
	s_add_u32 s100, s44, 0x80
	s_addc_u32 s101, s45, 0
	s_mov_b32 m0, s0
	ds_read_b128 v[184:187], v151 offset:49152
	ds_read_b128 v[188:191], v151 offset:50176
	ds_read_b128 v[192:195], v151 offset:51200
	ds_read_b128 v[196:199], v151 offset:52224
	global_load_lds_dwordx4 v130, s[100:101]
	s_add_i32 m0, s0, 0x2000
	s_add_u32 s0, s44, 0x100080
	s_addc_u32 s1, s45, 0
	s_add_i32 s44, s70, s49
	global_load_lds_dwordx4 v134, s[100:101]
	s_mov_b32 m0, s44
	ds_read_b128 v[218:221], v151 offset:56320
	global_load_lds_dwordx4 v130, s[0:1]
	s_add_i32 m0, s44, 0x2000
	ds_read_b128 v[214:217], v151 offset:55296
	global_load_lds_dwordx4 v134, s[0:1]
	s_add_u32 s100, s46, 0x80
	s_addc_u32 s101, s47, 0
	s_mov_b32 m0, s54
	ds_read_b128 v[210:213], v151 offset:54272
	global_load_lds_dwordx4 v128, s[100:101]
	s_mov_b32 m0, s55
	ds_read_b128 v[200:203], v151 offset:53248
	global_load_lds_dwordx4 v132, s[100:101]
	s_waitcnt vmcnt(8) lgkmcnt(0)
	s_setprio 3
	s_barrier
	v_mfma_f32_16x16x32_bf16 v[60:63], v[152:155], v[184:187], v[60:63]
	v_mfma_f32_16x16x32_bf16 v[56:59], v[160:163], v[184:187], v[56:59]
	v_mfma_f32_16x16x32_bf16 v[52:55], v[152:155], v[192:195], v[52:55]
	v_mfma_f32_16x16x32_bf16 v[44:47], v[160:163], v[192:195], v[44:47]
	v_mfma_f32_16x16x32_bf16 v[36:39], v[152:155], v[200:203], v[36:39]
	v_mfma_f32_16x16x32_bf16 v[28:31], v[160:163], v[200:203], v[28:31]
	v_mfma_f32_16x16x32_bf16 v[20:23], v[152:155], v[214:217], v[20:23]
	v_mfma_f32_16x16x32_bf16 v[12:15], v[160:163], v[214:217], v[12:15]
	v_mfma_f32_16x16x32_bf16 v[60:63], v[156:159], v[188:191], v[60:63]
	v_mfma_f32_16x16x32_bf16 v[56:59], v[164:167], v[188:191], v[56:59]
	v_mfma_f32_16x16x32_bf16 v[52:55], v[156:159], v[196:199], v[52:55]
	v_mfma_f32_16x16x32_bf16 v[44:47], v[164:167], v[196:199], v[44:47]
	v_mfma_f32_16x16x32_bf16 v[36:39], v[156:159], v[210:213], v[36:39]
	v_mfma_f32_16x16x32_bf16 v[28:31], v[164:167], v[210:213], v[28:31]
	v_mfma_f32_16x16x32_bf16 v[20:23], v[156:159], v[218:221], v[20:23]
	v_mfma_f32_16x16x32_bf16 v[12:15], v[164:167], v[218:221], v[12:15]
	s_add_u32 s42, s42, 0x100
	s_addc_u32 s43, s43, 0
	s_add_i32 s68, s68, 2
	s_add_u32 s66, s66, 0x100
	s_addc_u32 s67, s67, 0
	v_mfma_f32_16x16x32_bf16 v[48:51], v[168:171], v[184:187], v[48:51]
	v_mfma_f32_16x16x32_bf16 v[40:43], v[176:179], v[184:187], v[40:43]
	v_mfma_f32_16x16x32_bf16 v[32:35], v[168:171], v[192:195], v[32:35]
	v_mfma_f32_16x16x32_bf16 v[24:27], v[176:179], v[192:195], v[24:27]
	v_mfma_f32_16x16x32_bf16 v[16:19], v[168:171], v[200:203], v[16:19]
	v_mfma_f32_16x16x32_bf16 v[8:11], v[176:179], v[200:203], v[8:11]
	v_mfma_f32_16x16x32_bf16 v[4:7], v[168:171], v[214:217], v[4:7]
	v_mfma_f32_16x16x32_bf16 v[0:3], v[176:179], v[214:217], v[0:3]
	v_mfma_f32_16x16x32_bf16 v[48:51], v[172:175], v[188:191], v[48:51]
	v_mfma_f32_16x16x32_bf16 v[40:43], v[180:183], v[188:191], v[40:43]
	v_mfma_f32_16x16x32_bf16 v[32:35], v[172:175], v[196:199], v[32:35]
	v_mfma_f32_16x16x32_bf16 v[24:27], v[180:183], v[196:199], v[24:27]
	v_mfma_f32_16x16x32_bf16 v[16:19], v[172:175], v[210:213], v[16:19]
	v_mfma_f32_16x16x32_bf16 v[8:11], v[180:183], v[210:213], v[8:11]
	v_mfma_f32_16x16x32_bf16 v[4:7], v[172:175], v[218:221], v[4:7]
	v_mfma_f32_16x16x32_bf16 v[0:3], v[180:183], v[218:221], v[0:3]
	s_barrier
	s_setprio 0
	s_cmp_gt_u32 s68, 61
	s_cbranch_scc0 .LBB0_1637
	s_and_b64 vcc, exec, s[16:17]
	s_cbranch_vccz .LBB0_1640
	s_barrier

.LBB0_1813:
	ds_read_b128 v[148:151], v156
	ds_read_b128 v[160:163], v156 offset:1024
	ds_read_b128 v[164:167], v156 offset:2048
	ds_read_b128 v[168:171], v156 offset:3072
	ds_read_b128 v[172:175], v157
	ds_read_b128 v[176:179], v157 offset:1024
	ds_read_b128 v[180:183], v157 offset:2048
	ds_read_b128 v[184:187], v157 offset:3072
	s_add_u32 s0, s36, 0xfff00080
	s_addc_u32 s1, s37, -1
	s_cmp_eq_u32 s64, 60
	s_cselect_b32 s41, s59, s1
	s_cselect_b32 s40, s60, s0
	s_cselect_b32 s39, s17, s63
	s_cselect_b32 s38, s61, s62
	s_add_i32 m0, s31, 0xc000
	ds_read_b128 v[188:191], v158
	ds_read_b128 v[192:195], v158 offset:1024
	ds_read_b128 v[196:199], v158 offset:2048
	ds_read_b128 v[200:203], v158 offset:3072
	ds_read_b128 v[210:213], v158 offset:4096
	ds_read_b128 v[214:217], v158 offset:5120
	ds_read_b128 v[218:221], v158 offset:6144
	global_load_lds_dwordx4 v140, s[36:37]
	s_add_i32 m0, s31, 0xe000
	ds_read_b128 v[222:225], v158 offset:7168
	global_load_lds_dwordx4 v142, s[36:37]
	s_waitcnt vmcnt(8) lgkmcnt(0)
	s_setprio 3
	s_barrier
	v_mfma_f32_16x16x32_bf16 v[124:127], v[148:151], v[188:191], v[124:127]
	v_mfma_f32_16x16x32_bf16 v[120:123], v[164:167], v[188:191], v[120:123]
	v_mfma_f32_16x16x32_bf16 v[108:111], v[148:151], v[196:199], v[108:111]
	v_mfma_f32_16x16x32_bf16 v[104:107], v[164:167], v[196:199], v[104:107]
	v_mfma_f32_16x16x32_bf16 v[92:95], v[148:151], v[210:213], v[92:95]
	v_mfma_f32_16x16x32_bf16 v[88:91], v[164:167], v[210:213], v[88:91]
	v_mfma_f32_16x16x32_bf16 v[76:79], v[148:151], v[218:221], v[76:79]
	v_mfma_f32_16x16x32_bf16 v[72:75], v[164:167], v[218:221], v[72:75]
	v_mfma_f32_16x16x32_bf16 v[124:127], v[160:163], v[192:195], v[124:127]
	v_mfma_f32_16x16x32_bf16 v[120:123], v[168:171], v[192:195], v[120:123]
	v_mfma_f32_16x16x32_bf16 v[108:111], v[160:163], v[200:203], v[108:111]
	v_mfma_f32_16x16x32_bf16 v[104:107], v[168:171], v[200:203], v[104:107]
	v_mfma_f32_16x16x32_bf16 v[92:95], v[160:163], v[214:217], v[92:95]
	v_mfma_f32_16x16x32_bf16 v[88:91], v[168:171], v[214:217], v[88:91]
	v_mfma_f32_16x16x32_bf16 v[76:79], v[160:163], v[222:225], v[76:79]
	v_mfma_f32_16x16x32_bf16 v[72:75], v[168:171], v[222:225], v[72:75]
	v_mfma_f32_16x16x32_bf16 v[116:119], v[172:175], v[188:191], v[116:119]
	v_mfma_f32_16x16x32_bf16 v[112:115], v[180:183], v[188:191], v[112:115]
	v_mfma_f32_16x16x32_bf16 v[100:103], v[172:175], v[196:199], v[100:103]
	v_mfma_f32_16x16x32_bf16 v[96:99], v[180:183], v[196:199], v[96:99]
	v_mfma_f32_16x16x32_bf16 v[84:87], v[172:175], v[210:213], v[84:87]
	v_mfma_f32_16x16x32_bf16 v[80:83], v[180:183], v[210:213], v[80:83]
	v_mfma_f32_16x16x32_bf16 v[68:71], v[172:175], v[218:221], v[68:71]
	v_mfma_f32_16x16x32_bf16 v[64:67], v[180:183], v[218:221], v[64:67]
	v_mfma_f32_16x16x32_bf16 v[116:119], v[176:179], v[192:195], v[116:119]
	v_mfma_f32_16x16x32_bf16 v[112:115], v[184:187], v[192:195], v[112:115]
	v_mfma_f32_16x16x32_bf16 v[100:103], v[176:179], v[200:203], v[100:103]
	v_mfma_f32_16x16x32_bf16 v[96:99], v[184:187], v[200:203], v[96:99]
	v_mfma_f32_16x16x32_bf16 v[84:87], v[176:179], v[214:217], v[84:87]
	v_mfma_f32_16x16x32_bf16 v[80:83], v[184:187], v[214:217], v[80:83]
	v_mfma_f32_16x16x32_bf16 v[68:71], v[176:179], v[222:225], v[68:71]
	v_mfma_f32_16x16x32_bf16 v[64:67], v[184:187], v[222:225], v[64:67]
	s_barrier
	s_setprio 0
	s_add_i32 s0, s52, s43
	s_mov_b32 m0, s0
	ds_read_b128 v[188:191], v158 offset:16384
	ds_read_b128 v[192:195], v158 offset:17408
	ds_read_b128 v[196:199], v158 offset:18432
	ds_read_b128 v[200:203], v158 offset:19456
	ds_read_b128 v[210:213], v158 offset:20480
	global_load_lds_dwordx4 v132, s[38:39]
	s_add_i32 m0, s0, 0x2000
	s_add_u32 s0, s38, 0x100000
	s_addc_u32 s1, s39, 0
	s_add_i32 s65, s53, s43
	global_load_lds_dwordx4 v136, s[38:39]
	s_mov_b32 m0, s65
	s_nop 0
	global_load_lds_dwordx4 v132, s[0:1]
	s_add_i32 m0, s65, 0x2000
	ds_read_b128 v[222:225], v158 offset:23552
	global_load_lds_dwordx4 v136, s[0:1]
	s_mov_b32 m0, s31
	ds_read_b128 v[218:221], v158 offset:22528
	global_load_lds_dwordx4 v130, s[40:41]
	s_mov_b32 m0, s35
	ds_read_b128 v[214:217], v158 offset:21504
	global_load_lds_dwordx4 v134, s[40:41]
	s_waitcnt vmcnt(8) lgkmcnt(0)
	s_setprio 3
	s_barrier
	v_mfma_f32_16x16x32_bf16 v[60:63], v[148:151], v[188:191], v[60:63]
	v_mfma_f32_16x16x32_bf16 v[56:59], v[164:167], v[188:191], v[56:59]
	v_mfma_f32_16x16x32_bf16 v[44:47], v[148:151], v[196:199], v[44:47]
	v_mfma_f32_16x16x32_bf16 v[40:43], v[164:167], v[196:199], v[40:43]
	v_mfma_f32_16x16x32_bf16 v[28:31], v[148:151], v[210:213], v[28:31]
	v_mfma_f32_16x16x32_bf16 v[24:27], v[164:167], v[210:213], v[24:27]
	v_mfma_f32_16x16x32_bf16 v[12:15], v[148:151], v[218:221], v[12:15]
	v_mfma_f32_16x16x32_bf16 v[8:11], v[164:167], v[218:221], v[8:11]
	v_mfma_f32_16x16x32_bf16 v[60:63], v[160:163], v[192:195], v[60:63]
	v_mfma_f32_16x16x32_bf16 v[56:59], v[168:171], v[192:195], v[56:59]
	v_mfma_f32_16x16x32_bf16 v[44:47], v[160:163], v[200:203], v[44:47]
	v_mfma_f32_16x16x32_bf16 v[40:43], v[168:171], v[200:203], v[40:43]
	v_mfma_f32_16x16x32_bf16 v[28:31], v[160:163], v[214:217], v[28:31]
	v_mfma_f32_16x16x32_bf16 v[24:27], v[168:171], v[214:217], v[24:27]
	v_mfma_f32_16x16x32_bf16 v[12:15], v[160:163], v[222:225], v[12:15]
	v_mfma_f32_16x16x32_bf16 v[8:11], v[168:171], v[222:225], v[8:11]
	v_mfma_f32_16x16x32_bf16 v[52:55], v[172:175], v[188:191], v[52:55]
	v_mfma_f32_16x16x32_bf16 v[48:51], v[180:183], v[188:191], v[48:51]
	v_mfma_f32_16x16x32_bf16 v[36:39], v[172:175], v[196:199], v[36:39]
	v_mfma_f32_16x16x32_bf16 v[32:35], v[180:183], v[196:199], v[32:35]
	v_mfma_f32_16x16x32_bf16 v[20:23], v[172:175], v[210:213], v[20:23]
	v_mfma_f32_16x16x32_bf16 v[16:19], v[180:183], v[210:213], v[16:19]
	v_mfma_f32_16x16x32_bf16 v[4:7], v[172:175], v[218:221], v[4:7]
	v_mfma_f32_16x16x32_bf16 v[0:3], v[180:183], v[218:221], v[0:3]
	v_mfma_f32_16x16x32_bf16 v[52:55], v[176:179], v[192:195], v[52:55]
	v_mfma_f32_16x16x32_bf16 v[48:51], v[184:187], v[192:195], v[48:51]
	v_mfma_f32_16x16x32_bf16 v[36:39], v[176:179], v[200:203], v[36:39]
	v_mfma_f32_16x16x32_bf16 v[32:35], v[184:187], v[200:203], v[32:35]
	v_mfma_f32_16x16x32_bf16 v[20:23], v[176:179], v[214:217], v[20:23]
	v_mfma_f32_16x16x32_bf16 v[16:19], v[184:187], v[214:217], v[16:19]
	v_mfma_f32_16x16x32_bf16 v[4:7], v[176:179], v[222:225], v[4:7]
	v_mfma_f32_16x16x32_bf16 v[0:3], v[184:187], v[222:225], v[0:3]
	s_barrier
	s_setprio 0
	s_add_i32 s65, 0, 0x18000
	s_add_i32 s66, 0, 0x1c000
	ds_read_b128 v[148:151], v234
	ds_read_b128 v[160:163], v234 offset:1024
	ds_read_b128 v[164:167], v234 offset:2048
	ds_read_b128 v[168:171], v234 offset:3072
	ds_read_b128 v[172:175], v235
	ds_read_b128 v[176:179], v235 offset:1024
	ds_read_b128 v[180:183], v235 offset:2048
	ds_read_b128 v[184:187], v235 offset:3072
	s_add_u32 s0, s40, 0x100000
	s_addc_u32 s1, s41, 0
	s_mov_b32 m0, s44
	ds_read_b128 v[188:191], v158 offset:32768
	ds_read_b128 v[192:195], v158 offset:33792
	ds_read_b128 v[196:199], v158 offset:34816
	ds_read_b128 v[200:203], v158 offset:35840
	ds_read_b128 v[210:213], v158 offset:36864
	ds_read_b128 v[214:217], v158 offset:37888
	ds_read_b128 v[218:221], v158 offset:38912
	global_load_lds_dwordx4 v130, s[0:1]
	s_mov_b32 m0, s45
	ds_read_b128 v[222:225], v158 offset:39936
	global_load_lds_dwordx4 v134, s[0:1]
	s_waitcnt vmcnt(8) lgkmcnt(0)
	s_setprio 3
	s_barrier
	v_mfma_f32_16x16x32_bf16 v[124:127], v[148:151], v[188:191], v[124:127]
	v_mfma_f32_16x16x32_bf16 v[120:123], v[164:167], v[188:191], v[120:123]
	v_mfma_f32_16x16x32_bf16 v[108:111], v[148:151], v[196:199], v[108:111]
	v_mfma_f32_16x16x32_bf16 v[104:107], v[164:167], v[196:199], v[104:107]
	v_mfma_f32_16x16x32_bf16 v[92:95], v[148:151], v[210:213], v[92:95]
	v_mfma_f32_16x16x32_bf16 v[88:91], v[164:167], v[210:213], v[88:91]
	v_mfma_f32_16x16x32_bf16 v[76:79], v[148:151], v[218:221], v[76:79]
	v_mfma_f32_16x16x32_bf16 v[72:75], v[164:167], v[218:221], v[72:75]
	v_mfma_f32_16x16x32_bf16 v[124:127], v[160:163], v[192:195], v[124:127]
	v_mfma_f32_16x16x32_bf16 v[120:123], v[168:171], v[192:195], v[120:123]
	v_mfma_f32_16x16x32_bf16 v[108:111], v[160:163], v[200:203], v[108:111]
	v_mfma_f32_16x16x32_bf16 v[104:107], v[168:171], v[200:203], v[104:107]
	v_mfma_f32_16x16x32_bf16 v[92:95], v[160:163], v[214:217], v[92:95]
	v_mfma_f32_16x16x32_bf16 v[88:91], v[168:171], v[214:217], v[88:91]
	v_mfma_f32_16x16x32_bf16 v[76:79], v[160:163], v[222:225], v[76:79]
	v_mfma_f32_16x16x32_bf16 v[72:75], v[168:171], v[222:225], v[72:75]
	v_mfma_f32_16x16x32_bf16 v[116:119], v[172:175], v[188:191], v[116:119]
	v_mfma_f32_16x16x32_bf16 v[112:115], v[180:183], v[188:191], v[112:115]
	v_mfma_f32_16x16x32_bf16 v[100:103], v[172:175], v[196:199], v[100:103]
	v_mfma_f32_16x16x32_bf16 v[96:99], v[180:183], v[196:199], v[96:99]
	v_mfma_f32_16x16x32_bf16 v[84:87], v[172:175], v[210:213], v[84:87]
	v_mfma_f32_16x16x32_bf16 v[80:83], v[180:183], v[210:213], v[80:83]
	v_mfma_f32_16x16x32_bf16 v[68:71], v[172:175], v[218:221], v[68:71]
	v_mfma_f32_16x16x32_bf16 v[64:67], v[180:183], v[218:221], v[64:67]
	v_mfma_f32_16x16x32_bf16 v[116:119], v[176:179], v[192:195], v[116:119]
	v_mfma_f32_16x16x32_bf16 v[112:115], v[184:187], v[192:195], v[112:115]
	v_mfma_f32_16x16x32_bf16 v[100:103], v[176:179], v[200:203], v[100:103]
	v_mfma_f32_16x16x32_bf16 v[96:99], v[184:187], v[200:203], v[96:99]
	v_mfma_f32_16x16x32_bf16 v[84:87], v[176:179], v[214:217], v[84:87]
	v_mfma_f32_16x16x32_bf16 v[80:83], v[184:187], v[214:217], v[80:83]
	v_mfma_f32_16x16x32_bf16 v[68:71], v[176:179], v[222:225], v[68:71]
	v_mfma_f32_16x16x32_bf16 v[64:67], v[184:187], v[222:225], v[64:67]
	s_barrier
	s_setprio 0
	s_add_i32 s0, s65, s43
	s_add_u32 s100, s38, 0x80
	s_addc_u32 s101, s39, 0
	s_mov_b32 m0, s0
	ds_read_b128 v[188:191], v158 offset:49152
	ds_read_b128 v[192:195], v158 offset:50176
	ds_read_b128 v[196:199], v158 offset:51200
	ds_read_b128 v[200:203], v158 offset:52224
	global_load_lds_dwordx4 v132, s[100:101]
	s_add_i32 m0, s0, 0x2000
	s_add_u32 s0, s38, 0x100080
	s_addc_u32 s1, s39, 0
	s_add_i32 s38, s66, s43
	global_load_lds_dwordx4 v136, s[100:101]
	s_mov_b32 m0, s38
	ds_read_b128 v[222:225], v158 offset:56320
	global_load_lds_dwordx4 v132, s[0:1]
	s_add_i32 m0, s38, 0x2000
	ds_read_b128 v[218:221], v158 offset:55296
	global_load_lds_dwordx4 v136, s[0:1]
	s_add_u32 s100, s40, 0x80
	s_addc_u32 s101, s41, 0
	s_mov_b32 m0, s49
	ds_read_b128 v[214:217], v158 offset:54272
	global_load_lds_dwordx4 v130, s[100:101]
	s_mov_b32 m0, s50
	ds_read_b128 v[210:213], v158 offset:53248
	global_load_lds_dwordx4 v134, s[100:101]
	s_waitcnt vmcnt(8) lgkmcnt(0)
	s_setprio 3
	s_barrier
	v_mfma_f32_16x16x32_bf16 v[60:63], v[148:151], v[188:191], v[60:63]
	v_mfma_f32_16x16x32_bf16 v[56:59], v[164:167], v[188:191], v[56:59]
	v_mfma_f32_16x16x32_bf16 v[44:47], v[148:151], v[196:199], v[44:47]
	v_mfma_f32_16x16x32_bf16 v[40:43], v[164:167], v[196:199], v[40:43]
	v_mfma_f32_16x16x32_bf16 v[28:31], v[148:151], v[210:213], v[28:31]
	v_mfma_f32_16x16x32_bf16 v[24:27], v[164:167], v[210:213], v[24:27]
	v_mfma_f32_16x16x32_bf16 v[12:15], v[148:151], v[218:221], v[12:15]
	v_mfma_f32_16x16x32_bf16 v[8:11], v[164:167], v[218:221], v[8:11]
	v_mfma_f32_16x16x32_bf16 v[60:63], v[160:163], v[192:195], v[60:63]
	v_mfma_f32_16x16x32_bf16 v[56:59], v[168:171], v[192:195], v[56:59]
	v_mfma_f32_16x16x32_bf16 v[44:47], v[160:163], v[200:203], v[44:47]
	v_mfma_f32_16x16x32_bf16 v[40:43], v[168:171], v[200:203], v[40:43]
	v_mfma_f32_16x16x32_bf16 v[28:31], v[160:163], v[214:217], v[28:31]
	v_mfma_f32_16x16x32_bf16 v[24:27], v[168:171], v[214:217], v[24:27]
	v_mfma_f32_16x16x32_bf16 v[12:15], v[160:163], v[222:225], v[12:15]
	v_mfma_f32_16x16x32_bf16 v[8:11], v[168:171], v[222:225], v[8:11]
	s_add_u32 s36, s36, 0x100
	s_addc_u32 s37, s37, 0
	s_add_i32 s64, s64, 2
	s_add_u32 s62, s62, 0x100
	s_addc_u32 s63, s63, 0
	v_mfma_f32_16x16x32_bf16 v[52:55], v[172:175], v[188:191], v[52:55]
	v_mfma_f32_16x16x32_bf16 v[48:51], v[180:183], v[188:191], v[48:51]
	v_mfma_f32_16x16x32_bf16 v[36:39], v[172:175], v[196:199], v[36:39]
	v_mfma_f32_16x16x32_bf16 v[32:35], v[180:183], v[196:199], v[32:35]
	v_mfma_f32_16x16x32_bf16 v[20:23], v[172:175], v[210:213], v[20:23]
	v_mfma_f32_16x16x32_bf16 v[16:19], v[180:183], v[210:213], v[16:19]
	v_mfma_f32_16x16x32_bf16 v[4:7], v[172:175], v[218:221], v[4:7]
	v_mfma_f32_16x16x32_bf16 v[0:3], v[180:183], v[218:221], v[0:3]
	v_mfma_f32_16x16x32_bf16 v[52:55], v[176:179], v[192:195], v[52:55]
	v_mfma_f32_16x16x32_bf16 v[48:51], v[184:187], v[192:195], v[48:51]
	v_mfma_f32_16x16x32_bf16 v[36:39], v[176:179], v[200:203], v[36:39]
	v_mfma_f32_16x16x32_bf16 v[32:35], v[184:187], v[200:203], v[32:35]
	v_mfma_f32_16x16x32_bf16 v[20:23], v[176:179], v[214:217], v[20:23]
	v_mfma_f32_16x16x32_bf16 v[16:19], v[184:187], v[214:217], v[16:19]
	v_mfma_f32_16x16x32_bf16 v[4:7], v[176:179], v[222:225], v[4:7]
	v_mfma_f32_16x16x32_bf16 v[0:3], v[184:187], v[222:225], v[0:3]
	s_barrier
	s_setprio 0
	s_cmp_gt_u32 s64, 61
	s_cbranch_scc0 .LBB0_1813
	s_and_b64 vcc, exec, s[14:15]
	s_cbranch_vccz .LBB0_1816
	s_barrier
